# GEMM prologues: second K-tile's LDS-DMA loads issued before waiting for the first tile (one memory latency less per GEMM phase)
# speedup vs baseline: 1.0015x; 1.0015x over previous
; #define PG8_STAGE(bufoff, gbase, voff) do { _Pragma("unroll") for (int _i = 0; _i < 2; ++_i) \
;         __builtin_amdgcn_global_load_lds((const unsigned*)((const char*)(gbase) + (voff)[_i]), (PG8_LAS unsigned*)(lds + (bufoff) + ldsw + _i * 8192), 16, 0, 0); } while (0)
; #define PG8_WAIT_V(n) asm volatile("s_waitcnt vmcnt(" #n ")" ::: "memory")
; #define PG8_BAR __builtin_amdgcn_s_barrier()
; template <class Epi, class Sched, bool ALIGN_EPI = false, bool SP2 = false>
; __device__ __forceinline__ void gemm_phase(PG8_LAS unsigned char* lds, const Gemm g, const Sched& S, const Epi& E) {
;     ...
;     if constexpr (SP2) {
;         PG8_STAGE(PG8_SB(0, 0), cB, voffB); PG8_STAGE(PG8_SB(0, 1), cB + hstep, voffB); PG8_STAGE(PG8_SA(0, 0), cA, voffA); PG8_STAGE(PG8_SA(0, 1), cA + hstep, voffA);
;         if (wr == 1) PG8_BAR;
;         PG8_WAIT_V(2); PG8_BAR;
;         PG8_STAGE(PG8_SB(1, 0), cB + kstep, voffB); PG8_STAGE(PG8_SA(1, 0), cA + kstep, voffA); PG8_STAGE(PG8_SB(1, 1), cB + hstep + kstep, voffB);
;         PG8_WAIT_V(6); PG8_BAR;
.LBB0_276:
	s_add_u32 s4, s4, 0x1cc00000
	s_addc_u32 s5, s5, 0
	s_lshl_b32 s6, s6, 5
	s_and_b32 s44, s6, 0x60
	s_add_i32 m0, s30, 0x18000
	v_lshl_add_u64 v[8:9], v[8:9], 0, s[92:93]
	s_lshl_b32 s43, s7, 6
	s_lshl_b32 s13, s7, 13
	s_lshl_b32 s16, s44, 7
	global_load_lds_dwordx4 v[8:9], off
	v_lshl_add_u64 v[6:7], v[6:7], 0, s[92:93]
	s_add_i32 m0, s30, 0x1a000
	s_add_i32 s45, s30, 0x8000
	s_add_i32 s46, s30, 0xa000
	global_load_lds_dwordx4 v[6:7], off
	v_lshl_add_u64 v[2:3], v[2:3], 0, s[92:93]
	s_mov_b32 m0, s45
	s_add_u32 s6, s38, 0x40080
	global_load_lds_dwordx4 v[2:3], off
	v_lshl_add_u64 v[2:3], v[4:5], 0, s[92:93]
	s_mov_b32 m0, s46
	s_addc_u32 s7, s39, 0
	global_load_lds_dwordx4 v[2:3], off
	s_add_i32 m0, s30, 0x1c000
	v_lshl_add_u64 v[2:3], s[6:7], 0, v[0:1]
	global_load_lds_dwordx4 v[2:3], off
	v_lshl_add_u64 v[2:3], s[6:7], 0, v[130:131]
	s_add_i32 m0, s30, 0x1e000
	v_bfe_u32 v145, v10, 4, 2
	global_load_lds_dwordx4 v[2:3], off
	s_waitcnt vmcnt(8)
	s_barrier
	v_and_b32_e32 v144, 15, v10
	v_lshlrev_b32_e32 v2, 4, v145
	v_lshlrev_b32_e32 v3, 2, v10
	v_lshl_or_b32 v2, v144, 6, v2
	v_and_b32_e32 v3, 32, v3
	v_bitop3_b32 v4, v2, s13, v3 bitop3:0xde
	v_bitop3_b32 v146, v2, s16, v3 bitop3:0xde
	v_lshlrev_b32_e32 v2, 14, v15
	v_and_b32_e32 v2, 0xffff8000, v2
	v_lshl_add_u32 v2, v14, 11, v2
	v_and_b32_e32 v3, 1, v15
	v_lshl_or_b32 v2, v3, 6, v2
	v_lshl_add_u32 v136, v16, 1, v2
	v_lshlrev_b32_e32 v2, 14, v11
	s_cmpk_lt_u32 s12, 0x100
	v_and_b32_e32 v2, 0xffff8000, v2
	s_waitcnt vmcnt(6)
	s_cselect_b64 s[6:7], -1, 0
	s_and_b32 s12, s12, 0xffffff00
	v_lshl_add_u32 v2, v12, 11, v2
	v_and_b32_e32 v3, 1, v11
	s_add_i32 s47, s12, 0
	v_lshl_or_b32 v2, v3, 6, v2
	v_readlane_b32 s12, v254, 21
	s_add_i32 s47, s47, 0x20000
	v_mov_b32_e32 v137, v1
	v_lshl_add_u32 v138, v13, 1, v2
	v_mov_b32_e32 v139, v1
	s_mov_b32 s51, 0
	v_add_u32_e32 v147, 0, v4
	v_readlane_b32 s49, v254, 20
	s_mov_b32 s50, s12
	s_barrier
	v_readlane_b32 s13, v254, 22
	s_branch .LBB0_279

; #define PG8_STAGE(bufoff, gbase, voff) do { _Pragma("unroll") for (int _i = 0; _i < 2; ++_i) \
;         __builtin_amdgcn_global_load_lds((const unsigned*)((const char*)(gbase) + (voff)[_i]), (PG8_LAS unsigned*)(lds + (bufoff) + ldsw + _i * 8192), 16, 0, 0); } while (0)
; #define PG8_WAIT_V(n) asm volatile("s_waitcnt vmcnt(" #n ")" ::: "memory")
; #define PG8_BAR __builtin_amdgcn_s_barrier()
; template <class Epi, class Sched, bool ALIGN_EPI = false, bool SP2 = false>
; __device__ __forceinline__ void gemm_phase(PG8_LAS unsigned char* lds, const Gemm g, const Sched& S, const Epi& E) {
;     ...
;     if constexpr (SP2) {
;         PG8_STAGE(PG8_SB(0, 0), cB, voffB); PG8_STAGE(PG8_SB(0, 1), cB + hstep, voffB); PG8_STAGE(PG8_SA(0, 0), cA, voffA); PG8_STAGE(PG8_SA(0, 1), cA + hstep, voffA);
;         if (wr == 1) PG8_BAR;
;         PG8_WAIT_V(2); PG8_BAR;
;         PG8_STAGE(PG8_SB(1, 0), cB + kstep, voffB); PG8_STAGE(PG8_SA(1, 0), cA + kstep, voffA); PG8_STAGE(PG8_SB(1, 1), cB + hstep + kstep, voffB);
;         PG8_WAIT_V(6); PG8_BAR;
.LBB0_320:
	s_add_u32 s6, s6, 0xac00000
	s_addc_u32 s7, s7, 0
	s_lshl_b32 s86, s89, 6
	s_lshl_b64 s[30:31], s[86:87], 2
	s_add_u32 s40, s17, s30
	s_addc_u32 s41, s12, s31
	v_bfe_u32 v159, v16, 4, 2
	s_add_u32 s48, s24, s30
	v_and_b32_e32 v158, 15, v16
	v_lshlrev_b32_e32 v17, 4, v159
	v_lshlrev_b32_e32 v16, 2, v16
	s_addc_u32 s49, s13, s31
	s_and_b32 s50, s25, 3
	v_lshl_or_b32 v17, v158, 6, v17
	s_lshl_b32 s12, s5, 13
	v_and_b32_e32 v16, 32, v16
	s_add_i32 m0, s27, 0x18000
	v_lshl_add_u64 v[8:9], v[8:9], 0, s[92:93]
	s_lshl_b32 s51, s5, 6
	v_bitop3_b32 v18, v17, s12, v16 bitop3:0xde
	s_lshl_b32 s52, s50, 5
	s_lshl_b32 s12, s50, 12
	global_load_lds_dwordx4 v[8:9], off
	v_lshl_add_u64 v[6:7], v[6:7], 0, s[92:93]
	s_add_i32 m0, s27, 0x1a000
	s_add_i32 s53, s27, 0x8000
	s_add_i32 s54, s27, 0xa000
	v_bitop3_b32 v160, v17, s12, v16 bitop3:0xde
	global_load_lds_dwordx4 v[6:7], off
	v_lshl_add_u64 v[2:3], v[2:3], 0, s[92:93]
	s_mov_b32 m0, s53
	s_add_u32 s12, s22, 0x40080
	global_load_lds_dwordx4 v[2:3], off
	v_lshl_add_u64 v[2:3], v[4:5], 0, s[92:93]
	s_mov_b32 m0, s54
	s_addc_u32 s13, s23, 0
	global_load_lds_dwordx4 v[2:3], off
	s_add_i32 m0, s27, 0x1c000
	v_lshl_add_u64 v[2:3], s[12:13], 0, v[0:1]
	global_load_lds_dwordx4 v[2:3], off
	v_lshl_add_u64 v[2:3], s[12:13], 0, v[132:133]
	s_add_i32 m0, s27, 0x1e000
	s_cmpk_lt_u32 s4, 0x100
	global_load_lds_dwordx4 v[2:3], off
	s_waitcnt vmcnt(8)
	s_barrier
	v_lshlrev_b32_e32 v2, 14, v14
	v_and_b32_e32 v2, 0xffff8000, v2
	v_lshl_add_u32 v2, v13, 11, v2
	v_and_b32_e32 v3, 1, v14
	v_lshl_or_b32 v2, v3, 6, v2
	s_cselect_b64 s[12:13], -1, 0
	s_and_b32 s55, s4, 0xffffff00
	s_lshl_b32 s4, s5, 10
	s_lshl_b32 s5, s50, 2
	v_lshl_add_u32 v138, v15, 1, v2
	v_lshlrev_b32_e32 v2, 14, v10
	s_add_i32 s64, s5, 0
	v_and_b32_e32 v2, 0xffff8000, v2
	s_waitcnt vmcnt(6)
	s_add_i32 s64, s64, 0x23000
	v_lshl_add_u32 v2, v11, 11, v2
	v_and_b32_e32 v3, 1, v10
	s_add_i32 s65, s64, s4
	s_add_i32 s66, s55, 0
	v_lshl_or_b32 v2, v3, 6, v2
	v_readlane_b32 s4, v254, 37
	s_and_b32 s59, s52, 32
	s_add_i32 s66, s66, 0x20000
	v_mov_b32_e32 v139, v1
	v_lshl_add_u32 v140, v12, 1, v2
	v_mov_b32_e32 v141, v1
	s_mov_b32 s30, 0
	v_add_u32_e32 v161, 0, v18
	v_readlane_b32 s57, v254, 27
	s_mov_b32 s68, s4
	s_barrier
	v_readlane_b32 s5, v254, 38
	s_branch .LBB0_323

; #define PG8_STAGE(bufoff, gbase, voff) do { _Pragma("unroll") for (int _i = 0; _i < 2; ++_i) \
;         __builtin_amdgcn_global_load_lds((const unsigned*)((const char*)(gbase) + (voff)[_i]), (PG8_LAS unsigned*)(lds + (bufoff) + ldsw + _i * 8192), 16, 0, 0); } while (0)
; #define PG8_WAIT_V(n) asm volatile("s_waitcnt vmcnt(" #n ")" ::: "memory")
; #define PG8_BAR __builtin_amdgcn_s_barrier()
; template <class Epi, class Sched, bool ALIGN_EPI = false, bool SP2 = false>
; __device__ __forceinline__ void gemm_phase(PG8_LAS unsigned char* lds, const Gemm g, const Sched& S, const Epi& E) {
;     ...
;     if constexpr (SP2) {
;         PG8_STAGE(PG8_SB(0, 0), cB, voffB); PG8_STAGE(PG8_SB(0, 1), cB + hstep, voffB); PG8_STAGE(PG8_SA(0, 0), cA, voffA); PG8_STAGE(PG8_SA(0, 1), cA + hstep, voffA);
;         if (wr == 1) PG8_BAR;
;         PG8_WAIT_V(2); PG8_BAR;
;         PG8_STAGE(PG8_SB(1, 0), cB + kstep, voffB); PG8_STAGE(PG8_SA(1, 0), cA + kstep, voffA); PG8_STAGE(PG8_SB(1, 1), cB + hstep + kstep, voffB);
;         PG8_WAIT_V(6); PG8_BAR;
.LBB0_401:
	s_add_u32 s70, s14, 0xac00000
	s_addc_u32 s78, s15, 0
	s_lshl_b32 s86, s89, 6
	s_lshl_b64 s[10:11], s[86:87], 2
	s_add_u32 s12, s12, s10
	s_addc_u32 s13, s13, s11
	s_add_u32 s16, s16, s10
	s_addc_u32 s17, s17, s11
	v_bfe_u32 v157, v15, 4, 2
	s_add_u32 s14, s14, 0x1d900000
	v_and_b32_e32 v153, 15, v15
	v_lshlrev_b32_e32 v16, 4, v157
	v_lshlrev_b32_e32 v15, 2, v15
	s_addc_u32 s15, s15, 0
	s_and_b32 s68, s5, 3
	v_lshl_or_b32 v16, v153, 6, v16
	s_lshl_b32 s10, s40, 13
	v_and_b32_e32 v15, 32, v15
	s_add_i32 m0, s65, 0x18000
	v_lshl_add_u64 v[8:9], v[8:9], 0, s[92:93]
	s_lshl_b32 s55, s40, 6
	v_bitop3_b32 v17, v16, s10, v15 bitop3:0xde
	s_lshl_b32 s59, s68, 5
	s_lshl_b32 s10, s68, 12
	global_load_lds_dwordx4 v[8:9], off
	v_lshl_add_u64 v[6:7], v[6:7], 0, s[92:93]
	s_add_i32 m0, s65, 0x1a000
	s_add_i32 s69, s65, 0x8000
	s_add_i32 s54, s65, 0xa000
	v_bitop3_b32 v161, v16, s10, v15 bitop3:0xde
	global_load_lds_dwordx4 v[6:7], off
	v_lshl_add_u64 v[2:3], v[2:3], 0, s[92:93]
	s_mov_b32 m0, s69
	s_add_u32 s10, s20, 0x40080
	global_load_lds_dwordx4 v[2:3], off
	v_lshl_add_u64 v[2:3], v[4:5], 0, s[92:93]
	s_mov_b32 m0, s54
	s_addc_u32 s11, s21, 0
	global_load_lds_dwordx4 v[2:3], off
	s_add_i32 m0, s65, 0x1c000
	v_lshl_add_u64 v[2:3], s[10:11], 0, v[134:135]
	global_load_lds_dwordx4 v[2:3], off
	v_lshl_add_u64 v[2:3], s[10:11], 0, v[130:131]
	s_add_i32 m0, s65, 0x1e000
	s_cmpk_lt_u32 s4, 0x100
	global_load_lds_dwordx4 v[2:3], off
	s_waitcnt vmcnt(8)
	s_barrier
	v_lshlrev_b32_e32 v2, 14, v13
	v_and_b32_e32 v2, 0xffff8000, v2
	v_lshl_add_u32 v2, v12, 11, v2
	v_and_b32_e32 v3, 1, v13
	v_lshl_or_b32 v2, v3, 6, v2
	s_cselect_b64 s[44:45], -1, 0
	s_bfe_u32 s36, s5, 0x10001
	s_lshl_b32 s5, s68, 2
	v_lshl_add_u32 v138, v14, 1, v2
	v_lshlrev_b32_e32 v2, 14, v0
	s_add_i32 s28, s5, 0
	v_and_b32_e32 v2, 0xffff8000, v2
	s_waitcnt vmcnt(6)
	s_and_b32 s10, s4, 0xffffff00
	s_lshl_b32 s4, s40, 10
	s_add_i32 s28, s28, 0x23000
	v_lshl_add_u32 v2, v10, 11, v2
	v_and_b32_e32 v0, 1, v0
	s_add_i32 s79, s28, s4
	s_add_i32 s77, s10, 0
	v_lshl_or_b32 v0, v0, 6, v2
	v_readlane_b32 s4, v254, 43
	s_and_b32 s11, s59, 32
	s_add_i32 s77, s77, 0x20000
	v_mov_b32_e32 v139, v1
	v_lshl_add_u32 v140, v11, 1, v0
	v_mov_b32_e32 v141, v1
	s_mov_b32 s24, 0
	v_add_u32_e32 v184, 0, v17
	v_readlane_b32 s71, v254, 28
	s_mov_b32 s57, s4
	s_barrier
	v_readlane_b32 s5, v254, 44
	s_branch .LBB0_404

; #define PG8_STAGE(bufoff, gbase, voff) do { _Pragma("unroll") for (int _i = 0; _i < 2; ++_i) \
;         __builtin_amdgcn_global_load_lds((const unsigned*)((const char*)(gbase) + (voff)[_i]), (PG8_LAS unsigned*)(lds + (bufoff) + ldsw + _i * 8192), 16, 0, 0); } while (0)
; #define PG8_WAIT_V(n) asm volatile("s_waitcnt vmcnt(" #n ")" ::: "memory")
; #define PG8_BAR __builtin_amdgcn_s_barrier()
; template <class Epi, class Sched, bool ALIGN_EPI = false, bool SP2 = false>
; __device__ __forceinline__ void gemm_phase(PG8_LAS unsigned char* lds, const Gemm g, const Sched& S, const Epi& E) {
;     ...
;     if constexpr (SP2) {
;         PG8_STAGE(PG8_SB(0, 0), cB, voffB); PG8_STAGE(PG8_SB(0, 1), cB + hstep, voffB); PG8_STAGE(PG8_SA(0, 0), cA, voffA); PG8_STAGE(PG8_SA(0, 1), cA + hstep, voffA);
;         if (wr == 1) PG8_BAR;
;         PG8_WAIT_V(2); PG8_BAR;
;         PG8_STAGE(PG8_SB(1, 0), cB + kstep, voffB); PG8_STAGE(PG8_SA(1, 0), cA + kstep, voffA); PG8_STAGE(PG8_SB(1, 1), cB + hstep + kstep, voffB);
;         PG8_WAIT_V(6); PG8_BAR;
.LBB0_760:
	s_add_u32 s8, s7, 0x6c00000
	s_addc_u32 s9, s6, 0
	v_bfe_u32 v146, v15, 4, 2
	s_add_u32 s10, s7, 0x1d600000
	v_and_b32_e32 v147, 15, v15
	v_lshlrev_b32_e32 v17, 4, v146
	v_lshlrev_b32_e32 v15, 2, v15
	s_addc_u32 s11, s6, 0
	s_and_b32 s45, s12, 3
	s_lshl_b32 s46, s5, 6
	v_lshl_or_b32 v17, v147, 6, v17
	s_lshl_b32 s5, s5, 13
	v_and_b32_e32 v15, 32, v15
	s_add_i32 m0, s33, 0x18000
	v_lshl_add_u64 v[8:9], v[8:9], 0, s[92:93]
	v_bitop3_b32 v18, v17, s5, v15 bitop3:0xde
	s_lshl_b32 s47, s45, 5
	s_lshl_b32 s5, s45, 12
	global_load_lds_dwordx4 v[8:9], off
	v_lshl_add_u64 v[6:7], v[6:7], 0, s[92:93]
	s_add_i32 m0, s33, 0x1a000
	s_add_i32 s48, s33, 0x8000
	s_add_i32 s49, s33, 0xa000
	global_load_lds_dwordx4 v[6:7], off
	v_lshl_add_u64 v[2:3], v[2:3], 0, s[92:93]
	s_mov_b32 m0, s48
	s_add_u32 s6, s38, 0x40080
	global_load_lds_dwordx4 v[2:3], off
	v_lshl_add_u64 v[2:3], v[4:5], 0, s[92:93]
	s_mov_b32 m0, s49
	s_addc_u32 s7, s39, 0
	global_load_lds_dwordx4 v[2:3], off
	s_add_i32 m0, s33, 0x1c000
	v_lshl_add_u64 v[2:3], s[6:7], 0, v[0:1]
	global_load_lds_dwordx4 v[2:3], off
	v_lshl_add_u64 v[2:3], s[6:7], 0, v[130:131]
	s_add_i32 m0, s33, 0x1e000
	v_bitop3_b32 v148, v17, s5, v15 bitop3:0xde
	global_load_lds_dwordx4 v[2:3], off
	s_waitcnt vmcnt(8)
	s_barrier
	v_lshlrev_b32_e32 v2, 14, v14
	v_and_b32_e32 v2, 0xffff8000, v2
	v_lshl_add_u32 v2, v13, 11, v2
	v_and_b32_e32 v3, 1, v14
	v_lshl_or_b32 v2, v3, 6, v2
	v_lshl_add_u32 v136, v16, 1, v2
	v_lshlrev_b32_e32 v2, 14, v10
	v_and_b32_e32 v2, 0xffff8000, v2
	s_waitcnt vmcnt(6)
	v_lshl_add_u32 v2, v11, 11, v2
	v_and_b32_e32 v3, 1, v10
	s_cmpk_lt_u32 s4, 0x100
	v_lshl_or_b32 v2, v3, 6, v2
	v_readlane_b32 s4, v255, 1
	s_cselect_b64 s[12:13], -1, 0
	v_mov_b32_e32 v137, v1
	v_lshl_add_u32 v138, v12, 1, v2
	v_mov_b32_e32 v139, v1
	s_mov_b32 s50, 0
	v_add_u32_e32 v149, 0, v18
	v_readlane_b32 s51, v255, 5
	s_mov_b32 s52, s4
	s_barrier
	v_readlane_b32 s5, v255, 2
	s_branch .LBB0_763

; #define PG8_STAGE(bufoff, gbase, voff) do { _Pragma("unroll") for (int _i = 0; _i < 2; ++_i) \
;         __builtin_amdgcn_global_load_lds((const unsigned*)((const char*)(gbase) + (voff)[_i]), (PG8_LAS unsigned*)(lds + (bufoff) + ldsw + _i * 8192), 16, 0, 0); } while (0)
; #define PG8_WAIT_V(n) asm volatile("s_waitcnt vmcnt(" #n ")" ::: "memory")
; #define PG8_BAR __builtin_amdgcn_s_barrier()
; template <class Epi, class Sched, bool ALIGN_EPI = false, bool SP2 = false>
; __device__ __forceinline__ void gemm_phase(PG8_LAS unsigned char* lds, const Gemm g, const Sched& S, const Epi& E) {
;     ...
;     if constexpr (SP2) {
;         PG8_STAGE(PG8_SB(0, 0), cB, voffB); PG8_STAGE(PG8_SB(0, 1), cB + hstep, voffB); PG8_STAGE(PG8_SA(0, 0), cA, voffA); PG8_STAGE(PG8_SA(0, 1), cA + hstep, voffA);
;         if (wr == 1) PG8_BAR;
;         PG8_WAIT_V(2); PG8_BAR;
;         PG8_STAGE(PG8_SB(1, 0), cB + kstep, voffB); PG8_STAGE(PG8_SA(1, 0), cA + kstep, voffA); PG8_STAGE(PG8_SB(1, 1), cB + hstep + kstep, voffB);
;         PG8_WAIT_V(6); PG8_BAR;
.LBB0_892:
	s_add_u32 s8, s8, 0x1ac00000
	s_addc_u32 s9, s7, 0
	v_bfe_u32 v145, v16, 4, 2
	s_lshl_b32 s5, s5, 5
	v_and_b32_e32 v144, 15, v16
	v_lshlrev_b32_e32 v17, 4, v145
	v_lshlrev_b32_e32 v16, 2, v16
	s_and_b32 s44, s5, 0x60
	s_add_i32 m0, s33, 0x18000
	v_lshl_add_u64 v[8:9], v[8:9], 0, s[92:93]
	s_lshl_b32 s43, s6, 6
	v_lshl_or_b32 v17, v144, 6, v17
	s_lshl_b32 s6, s6, 13
	v_and_b32_e32 v16, 32, v16
	s_lshl_b32 s5, s44, 7
	global_load_lds_dwordx4 v[8:9], off
	v_lshl_add_u64 v[6:7], v[6:7], 0, s[92:93]
	s_add_i32 m0, s33, 0x1a000
	s_add_i32 s45, s33, 0x8000
	s_add_i32 s46, s33, 0xa000
	v_bitop3_b32 v18, v17, s6, v16 bitop3:0xde
	global_load_lds_dwordx4 v[6:7], off
	v_lshl_add_u64 v[2:3], v[2:3], 0, s[92:93]
	s_mov_b32 m0, s45
	s_add_u32 s6, s26, 0x40080
	global_load_lds_dwordx4 v[2:3], off
	v_lshl_add_u64 v[2:3], v[4:5], 0, s[92:93]
	s_mov_b32 m0, s46
	s_addc_u32 s7, s27, 0
	global_load_lds_dwordx4 v[2:3], off
	s_add_i32 m0, s33, 0x1c000
	v_lshl_add_u64 v[2:3], s[6:7], 0, v[0:1]
	global_load_lds_dwordx4 v[2:3], off
	v_lshl_add_u64 v[2:3], s[6:7], 0, v[130:131]
	s_add_i32 m0, s33, 0x1e000
	s_cmpk_lt_u32 s4, 0x100
	global_load_lds_dwordx4 v[2:3], off
	s_waitcnt vmcnt(8)
	s_barrier
	v_lshlrev_b32_e32 v2, 14, v14
	v_and_b32_e32 v2, 0xffff8000, v2
	v_lshl_add_u32 v2, v13, 11, v2
	v_and_b32_e32 v3, 1, v14
	v_lshl_or_b32 v2, v3, 6, v2
	v_lshl_add_u32 v136, v15, 1, v2
	v_lshlrev_b32_e32 v2, 14, v10
	v_and_b32_e32 v2, 0xffff8000, v2
	s_waitcnt vmcnt(6)
	s_cselect_b64 s[10:11], -1, 0
	s_and_b32 s4, s4, 0xffffff00
	v_lshl_add_u32 v2, v11, 11, v2
	v_and_b32_e32 v3, 1, v10
	v_bitop3_b32 v146, v17, s5, v16 bitop3:0xde
	s_add_i32 s47, s4, 0
	v_lshl_or_b32 v2, v3, 6, v2
	v_readlane_b32 s4, v254, 30
	s_add_i32 s47, s47, 0x20000
	v_mov_b32_e32 v137, v1
	v_lshl_add_u32 v138, v12, 1, v2
	v_mov_b32_e32 v139, v1
	s_mov_b32 s51, 0
	v_add_u32_e32 v147, 0, v18
	v_readlane_b32 s49, v254, 29
	s_mov_b32 s50, s4
	s_barrier
	v_readlane_b32 s5, v254, 31
	s_branch .LBB0_895

; #define PG8_STAGE(bufoff, gbase, voff) do { _Pragma("unroll") for (int _i = 0; _i < 2; ++_i) \
;         __builtin_amdgcn_global_load_lds((const unsigned*)((const char*)(gbase) + (voff)[_i]), (PG8_LAS unsigned*)(lds + (bufoff) + ldsw + _i * 8192), 16, 0, 0); } while (0)
; #define PG8_WAIT_V(n) asm volatile("s_waitcnt vmcnt(" #n ")" ::: "memory")
; #define PG8_BAR __builtin_amdgcn_s_barrier()
; template <class Epi, class Sched, bool ALIGN_EPI = false, bool SP2 = false>
; __device__ __forceinline__ void gemm_phase(PG8_LAS unsigned char* lds, const Gemm g, const Sched& S, const Epi& E) {
;     ...
;     if constexpr (SP2) {
;         PG8_STAGE(PG8_SB(0, 0), cB, voffB); PG8_STAGE(PG8_SB(0, 1), cB + hstep, voffB); PG8_STAGE(PG8_SA(0, 0), cA, voffA); PG8_STAGE(PG8_SA(0, 1), cA + hstep, voffA);
;         if (wr == 1) PG8_BAR;
;         PG8_WAIT_V(2); PG8_BAR;
;         PG8_STAGE(PG8_SB(1, 0), cB + kstep, voffB); PG8_STAGE(PG8_SA(1, 0), cA + kstep, voffA); PG8_STAGE(PG8_SB(1, 1), cB + hstep + kstep, voffB);
;         PG8_WAIT_V(6); PG8_BAR;
.LBB0_1053:
	s_add_u32 s8, s7, 0x6c00000
	s_addc_u32 s9, s6, 0
	v_bfe_u32 v146, v16, 4, 2
	s_add_u32 s10, s7, 0x1d600000
	v_and_b32_e32 v147, 15, v16
	v_lshlrev_b32_e32 v17, 4, v146
	v_lshlrev_b32_e32 v16, 2, v16
	s_addc_u32 s11, s6, 0
	s_and_b32 s45, s12, 3
	s_lshl_b32 s46, s5, 6
	v_lshl_or_b32 v17, v147, 6, v17
	s_lshl_b32 s5, s5, 13
	v_and_b32_e32 v16, 32, v16
	s_add_i32 m0, s33, 0x18000
	v_lshl_add_u64 v[8:9], v[8:9], 0, s[92:93]
	v_bitop3_b32 v18, v17, s5, v16 bitop3:0xde
	s_lshl_b32 s47, s45, 5
	s_lshl_b32 s5, s45, 12
	global_load_lds_dwordx4 v[8:9], off
	v_lshl_add_u64 v[6:7], v[6:7], 0, s[92:93]
	s_add_i32 m0, s33, 0x1a000
	s_add_i32 s48, s33, 0x8000
	s_add_i32 s49, s33, 0xa000
	global_load_lds_dwordx4 v[6:7], off
	v_lshl_add_u64 v[2:3], v[2:3], 0, s[92:93]
	s_mov_b32 m0, s48
	s_add_u32 s6, s38, 0x20080
	global_load_lds_dwordx4 v[2:3], off
	v_lshl_add_u64 v[2:3], v[4:5], 0, s[92:93]
	s_mov_b32 m0, s49
	s_addc_u32 s7, s39, 0
	global_load_lds_dwordx4 v[2:3], off
	s_add_i32 m0, s33, 0x1c000
	v_lshl_add_u64 v[2:3], s[6:7], 0, v[0:1]
	global_load_lds_dwordx4 v[2:3], off
	v_lshl_add_u64 v[2:3], s[6:7], 0, v[130:131]
	s_add_i32 m0, s33, 0x1e000
	v_bitop3_b32 v148, v17, s5, v16 bitop3:0xde
	global_load_lds_dwordx4 v[2:3], off
	s_waitcnt vmcnt(8)
	s_barrier
	v_lshlrev_b32_e32 v2, 13, v14
	v_and_b32_e32 v2, 0xffffc000, v2
	v_lshl_add_u32 v2, v13, 10, v2
	v_and_b32_e32 v3, 1, v14
	v_lshl_or_b32 v2, v3, 6, v2
	v_lshl_add_u32 v136, v15, 1, v2
	v_lshlrev_b32_e32 v2, 13, v10
	v_and_b32_e32 v2, 0xffffc000, v2
	s_waitcnt vmcnt(6)
	v_lshl_add_u32 v2, v11, 10, v2
	v_and_b32_e32 v3, 1, v10
	s_cmpk_lt_u32 s4, 0x100
	v_lshl_or_b32 v2, v3, 6, v2
	v_readlane_b32 s4, v255, 1
	s_cselect_b64 s[12:13], -1, 0
	v_mov_b32_e32 v137, v1
	v_lshl_add_u32 v138, v12, 1, v2
	v_mov_b32_e32 v139, v1
	s_mov_b32 s50, 0
	v_add_u32_e32 v149, 0, v18
	v_readlane_b32 s51, v255, 5
	s_mov_b32 s52, s4
	s_barrier
	v_readlane_b32 s5, v255, 2
	s_branch .LBB0_1056

; #define PG8_STAGE(bufoff, gbase, voff) do { _Pragma("unroll") for (int _i = 0; _i < 2; ++_i) \
;         __builtin_amdgcn_global_load_lds((const unsigned*)((const char*)(gbase) + (voff)[_i]), (PG8_LAS unsigned*)(lds + (bufoff) + ldsw + _i * 8192), 16, 0, 0); } while (0)
; #define PG8_WAIT_V(n) asm volatile("s_waitcnt vmcnt(" #n ")" ::: "memory")
; #define PG8_BAR __builtin_amdgcn_s_barrier()
; template <class Epi, class Sched, bool ALIGN_EPI = false, bool SP2 = false>
; __device__ __forceinline__ void gemm_phase(PG8_LAS unsigned char* lds, const Gemm g, const Sched& S, const Epi& E) {
;     ...
;     if constexpr (SP2) {
;         PG8_STAGE(PG8_SB(0, 0), cB, voffB); PG8_STAGE(PG8_SB(0, 1), cB + hstep, voffB); PG8_STAGE(PG8_SA(0, 0), cA, voffA); PG8_STAGE(PG8_SA(0, 1), cA + hstep, voffA);
;         if (wr == 1) PG8_BAR;
;         PG8_WAIT_V(2); PG8_BAR;
;         PG8_STAGE(PG8_SB(1, 0), cB + kstep, voffB); PG8_STAGE(PG8_SA(1, 0), cA + kstep, voffA); PG8_STAGE(PG8_SB(1, 1), cB + hstep + kstep, voffB);
;         PG8_WAIT_V(6); PG8_BAR;
.LBB0_1169:
	s_add_u32 s38, s12, 0xac00000
	s_mul_i32 s5, s74, 0x10800
	s_addc_u32 s39, s11, 0
	s_mul_hi_u32 s4, s74, 0x10800
	s_add_u32 s44, s22, s5
	s_mul_i32 s24, s74, 0x5800
	s_addc_u32 s45, s20, s4
	s_mul_hi_u32 s23, s74, 0x5800
	s_add_u32 s46, s21, s24
	s_addc_u32 s47, s13, s23
	v_bfe_u32 v207, v16, 4, 2
	s_add_u32 s48, s12, 0x1da00000
	v_and_b32_e32 v206, 15, v16
	v_lshlrev_b32_e32 v17, 4, v207
	v_lshlrev_b32_e32 v16, 2, v16
	s_addc_u32 s49, s11, 0
	v_lshl_or_b32 v17, v206, 6, v17
	s_lshl_b32 s4, s7, 13
	v_and_b32_e32 v16, 32, v16
	v_bitop3_b32 v18, v17, s4, v16 bitop3:0xde
	s_lshl_b32 s4, s10, 5
	s_and_b32 s69, s4, 0x60
	s_add_i32 m0, s54, 0x18000
	v_lshl_add_u64 v[8:9], v[8:9], 0, s[92:93]
	s_lshl_b32 s68, s7, 6
	s_lshl_b32 s4, s69, 7
	global_load_lds_dwordx4 v[8:9], off
	v_lshl_add_u64 v[6:7], v[6:7], 0, s[92:93]
	s_add_i32 m0, s54, 0x1a000
	s_add_i32 s70, s54, 0x8000
	s_add_i32 s71, s54, 0xa000
	v_bitop3_b32 v208, v17, s4, v16 bitop3:0xde
	global_load_lds_dwordx4 v[6:7], off
	v_lshl_add_u64 v[2:3], v[2:3], 0, s[92:93]
	s_mov_b32 m0, s70
	s_add_u32 s4, s8, 0x40080
	global_load_lds_dwordx4 v[2:3], off
	v_lshl_add_u64 v[2:3], v[4:5], 0, s[92:93]
	s_mov_b32 m0, s71
	s_addc_u32 s5, s9, 0
	global_load_lds_dwordx4 v[2:3], off
	s_add_i32 m0, s54, 0x1c000
	v_lshl_add_u64 v[2:3], s[4:5], 0, v[0:1]
	global_load_lds_dwordx4 v[2:3], off
	v_lshl_add_u64 v[2:3], s[4:5], 0, v[156:157]
	s_add_i32 m0, s54, 0x1e000
	s_cmpk_lt_u32 s6, 0x100
	global_load_lds_dwordx4 v[2:3], off
	s_waitcnt vmcnt(8)
	s_barrier
	s_cselect_b64 s[50:51], -1, 0
	s_lshl_b32 s77, s7, 1
	s_and_b32 s4, s6, 0xffffff00
	s_add_i32 s77, s77, 0x3ffff2
	s_cmp_gt_i32 s7, 0
	s_cselect_b64 s[52:53], -1, 0
	s_lshl_b32 s5, s7, 11
	s_cmp_gt_i32 s7, -2
	s_cselect_b64 s[40:41], -1, 0
	s_lshl_b32 s6, s69, 2
	v_lshlrev_b32_e32 v2, 14, v14
	s_add_i32 s79, s6, 0
	v_and_b32_e32 v2, 0xffff8000, v2
	s_add_i32 s78, s79, 0x24000
	v_lshl_add_u32 v2, v13, 11, v2
	v_and_b32_e32 v3, 1, v14
	s_add_u32 s20, s44, 0x5800
	v_lshl_or_b32 v2, v3, 6, v2
	s_addc_u32 s21, s45, 0
	v_lshl_add_u32 v182, v15, 1, v2
	v_lshlrev_b32_e32 v2, 14, v10
	s_add_u32 s22, s44, 0xb000
	v_and_b32_e32 v2, 0xffff8000, v2
	s_waitcnt vmcnt(6)
	s_addc_u32 s23, s45, 0
	s_add_i32 s79, s79, 0x23000
	v_lshl_add_u32 v2, v11, 11, v2
	v_and_b32_e32 v3, 1, v10
	s_add_i32 s86, s79, s5
	s_add_i32 s94, s4, 0
	v_lshl_or_b32 v2, v3, 6, v2
	v_readlane_b32 s4, v254, 57
	s_mov_b32 s13, 0
	s_add_i32 s62, s86, 0xfffffc00
	s_add_i32 s31, s86, 0xfffff800
	s_add_i32 s30, s86, 0xfffffe00
	s_add_i32 s43, s86, 0xfffffa00
	s_add_i32 s94, s94, 0x20000
	v_mov_b32_e32 v183, v1
	v_lshl_add_u32 v184, v12, 1, v2
	v_mov_b32_e32 v185, v1
	v_add_u32_e32 v209, 0, v18
	v_readlane_b32 s12, v254, 36
	s_mov_b32 s76, s4
	s_barrier
	v_readlane_b32 s5, v254, 58
	s_branch .LBB0_1172

; #define PG8_STAGE(bufoff, gbase, voff) do { _Pragma("unroll") for (int _i = 0; _i < 2; ++_i) \
;         __builtin_amdgcn_global_load_lds((const unsigned*)((const char*)(gbase) + (voff)[_i]), (PG8_LAS unsigned*)(lds + (bufoff) + ldsw + _i * 8192), 16, 0, 0); } while (0)
; #define PG8_WAIT_V(n) asm volatile("s_waitcnt vmcnt(" #n ")" ::: "memory")
; #define PG8_BAR __builtin_amdgcn_s_barrier()
; template <class Epi, class Sched, bool ALIGN_EPI = false, bool SP2 = false>
; __device__ __forceinline__ void gemm_phase(PG8_LAS unsigned char* lds, const Gemm g, const Sched& S, const Epi& E) {
;     ...
;     if constexpr (SP2) {
;         PG8_STAGE(PG8_SB(0, 0), cB, voffB); PG8_STAGE(PG8_SB(0, 1), cB + hstep, voffB); PG8_STAGE(PG8_SA(0, 0), cA, voffA); PG8_STAGE(PG8_SA(0, 1), cA + hstep, voffA);
;         if (wr == 1) PG8_BAR;
;         PG8_WAIT_V(2); PG8_BAR;
;         PG8_STAGE(PG8_SB(1, 0), cB + kstep, voffB); PG8_STAGE(PG8_SA(1, 0), cA + kstep, voffA); PG8_STAGE(PG8_SB(1, 1), cB + hstep + kstep, voffB);
;         PG8_WAIT_V(6); PG8_BAR;
.LBB0_1284:
	s_add_u32 s12, s5, 0x6c00000
	s_addc_u32 s13, s4, 0
	v_bfe_u32 v148, v18, 4, 2
	s_add_u32 s16, s5, 0x1d600000
	v_and_b32_e32 v149, 15, v18
	v_lshlrev_b32_e32 v19, 4, v148
	v_lshlrev_b32_e32 v18, 2, v18
	s_addc_u32 s17, s4, 0
	s_and_b32 s33, s6, 3
	s_lshl_b32 s36, s1, 6
	v_lshl_or_b32 v19, v149, 6, v19
	s_lshl_b32 s1, s1, 13
	v_and_b32_e32 v18, 32, v18
	s_add_i32 m0, s15, 0x18000
	v_lshl_add_u64 v[8:9], v[8:9], 0, s[92:93]
	v_bitop3_b32 v20, v19, s1, v18 bitop3:0xde
	s_lshl_b32 s43, s33, 5
	s_lshl_b32 s1, s33, 12
	global_load_lds_dwordx4 v[8:9], off
	v_lshl_add_u64 v[6:7], v[6:7], 0, s[92:93]
	s_add_i32 m0, s15, 0x1a000
	s_add_i32 s48, s15, 0x8000
	s_add_i32 s49, s15, 0xa000
	global_load_lds_dwordx4 v[6:7], off
	v_lshl_add_u64 v[2:3], v[2:3], 0, s[92:93]
	s_mov_b32 m0, s48
	s_add_u32 s4, s26, 0xb0080
	global_load_lds_dwordx4 v[2:3], off
	v_lshl_add_u64 v[2:3], v[4:5], 0, s[92:93]
	s_mov_b32 m0, s49
	s_addc_u32 s5, s27, 0
	global_load_lds_dwordx4 v[2:3], off
	s_add_i32 m0, s15, 0x1c000
	v_lshl_add_u64 v[2:3], s[4:5], 0, v[0:1]
	global_load_lds_dwordx4 v[2:3], off
	v_lshl_add_u64 v[2:3], s[4:5], 0, v[132:133]
	s_add_i32 m0, s15, 0x1e000
	s_mov_b32 s4, 0xb000
	global_load_lds_dwordx4 v[2:3], off
	s_waitcnt vmcnt(8)
	s_barrier
	v_lshrrev_b32_e32 v3, 1, v15
	v_mul_lo_u32 v2, v14, s37
	v_bitop3_b32 v150, v19, s1, v18 bitop3:0xde
	s_cmpk_lt_u32 s0, 0x100
	v_mad_u64_u32 v[2:3], s[0:1], v3, s4, v[2:3]
	v_or_b32_e32 v2, v2, v16
	v_add_lshl_u32 v2, v2, v17, 1
	v_mov_b32_e32 v3, v1
	s_mov_b64 s[6:7], 0xb0080
	v_lshl_add_u64 v[138:139], v[2:3], 0, s[6:7]
	v_lshrrev_b32_e32 v3, 1, v10
	v_mul_lo_u32 v2, v11, s37
	v_mad_u64_u32 v[2:3], s[0:1], v3, s4, v[2:3]
	s_waitcnt vmcnt(6)
	v_or_b32_e32 v2, v2, v12
	v_add_lshl_u32 v2, v2, v13, 1
	v_mov_b32_e32 v3, v1
	v_readlane_b32 s0, v255, 1
	s_cselect_b64 s[20:21], -1, 0
	v_lshl_add_u64 v[140:141], v[2:3], 0, s[6:7]
	s_mov_b32 s50, 0
	v_add_u32_e32 v151, 0, v20
	v_readlane_b32 s53, v255, 5
	s_mov_b32 s54, s0
	s_barrier
	v_readlane_b32 s1, v255, 2
	s_branch .LBB0_1287

; #define PG8_STAGE(bufoff, gbase, voff) do { _Pragma("unroll") for (int _i = 0; _i < 2; ++_i) \
;         __builtin_amdgcn_global_load_lds((const unsigned*)((const char*)(gbase) + (voff)[_i]), (PG8_LAS unsigned*)(lds + (bufoff) + ldsw + _i * 8192), 16, 0, 0); } while (0)
; #define PG8_WAIT_V(n) asm volatile("s_waitcnt vmcnt(" #n ")" ::: "memory")
; #define PG8_BAR __builtin_amdgcn_s_barrier()
; template <class Epi, class Sched, bool ALIGN_EPI = false, bool SP2 = false>
; __device__ __forceinline__ void gemm_phase(PG8_LAS unsigned char* lds, const Gemm g, const Sched& S, const Epi& E) {
;     ...
;     if constexpr (SP2) {
;         PG8_STAGE(PG8_SB(0, 0), cB, voffB); PG8_STAGE(PG8_SB(0, 1), cB + hstep, voffB); PG8_STAGE(PG8_SA(0, 0), cA, voffA); PG8_STAGE(PG8_SA(0, 1), cA + hstep, voffA);
;         if (wr == 1) PG8_BAR;
;         PG8_WAIT_V(2); PG8_BAR;
;         PG8_STAGE(PG8_SB(1, 0), cB + kstep, voffB); PG8_STAGE(PG8_SA(1, 0), cA + kstep, voffA); PG8_STAGE(PG8_SB(1, 1), cB + hstep + kstep, voffB);
;         PG8_WAIT_V(6); PG8_BAR;
.LBB0_1326:
	s_add_u32 s12, s5, 0x6c00000
	s_addc_u32 s13, s4, 0
	v_bfe_u32 v147, v18, 4, 2
	s_add_u32 s16, s5, 0x1d600000
	v_and_b32_e32 v146, 15, v18
	v_lshlrev_b32_e32 v19, 4, v147
	v_lshlrev_b32_e32 v18, 2, v18
	s_addc_u32 s17, s4, 0
	s_and_b32 s33, s20, 3
	s_lshl_b32 s36, s1, 6
	v_lshl_or_b32 v19, v146, 6, v19
	s_lshl_b32 s1, s1, 13
	v_and_b32_e32 v18, 32, v18
	s_add_i32 m0, s15, 0x18000
	v_lshl_add_u64 v[8:9], v[8:9], 0, s[92:93]
	v_bitop3_b32 v20, v19, s1, v18 bitop3:0xde
	s_lshl_b32 s43, s33, 5
	s_lshl_b32 s1, s33, 12
	global_load_lds_dwordx4 v[8:9], off
	v_lshl_add_u64 v[6:7], v[6:7], 0, s[92:93]
	s_add_i32 m0, s15, 0x1a000
	s_add_i32 s48, s15, 0x8000
	s_add_i32 s49, s15, 0xa000
	global_load_lds_dwordx4 v[6:7], off
	v_lshl_add_u64 v[2:3], v[2:3], 0, s[92:93]
	s_mov_b32 m0, s48
	s_add_u32 s4, s26, 0xb0080
	global_load_lds_dwordx4 v[2:3], off
	v_lshl_add_u64 v[2:3], v[4:5], 0, s[92:93]
	s_mov_b32 m0, s49
	s_addc_u32 s5, s27, 0
	global_load_lds_dwordx4 v[2:3], off
	s_add_i32 m0, s15, 0x1c000
	v_lshl_add_u64 v[2:3], s[4:5], 0, v[0:1]
	global_load_lds_dwordx4 v[2:3], off
	v_lshl_add_u64 v[2:3], s[4:5], 0, v[130:131]
	s_add_i32 m0, s15, 0x1e000
	s_mov_b32 s4, 0xb000
	global_load_lds_dwordx4 v[2:3], off
	s_waitcnt vmcnt(8)
	s_barrier
	v_lshrrev_b32_e32 v3, 1, v15
	v_mul_lo_u32 v2, v14, s37
	v_bitop3_b32 v148, v19, s1, v18 bitop3:0xde
	s_cmpk_lt_u32 s0, 0x100
	v_mad_u64_u32 v[2:3], s[0:1], v3, s4, v[2:3]
	v_or_b32_e32 v2, v2, v16
	v_add_lshl_u32 v2, v2, v17, 1
	v_mov_b32_e32 v3, v1
	s_mov_b64 s[22:23], 0xb0080
	v_lshl_add_u64 v[136:137], v[2:3], 0, s[22:23]
	v_lshrrev_b32_e32 v3, 1, v10
	v_mul_lo_u32 v2, v11, s37
	v_mad_u64_u32 v[2:3], s[0:1], v3, s4, v[2:3]
	s_waitcnt vmcnt(6)
	v_or_b32_e32 v2, v2, v12
	v_add_lshl_u32 v2, v2, v13, 1
	v_mov_b32_e32 v3, v1
	v_readlane_b32 s0, v255, 1
	s_cselect_b64 s[20:21], -1, 0
	v_lshl_add_u64 v[138:139], v[2:3], 0, s[22:23]
	s_mov_b32 s50, 0
	v_add_u32_e32 v149, 0, v20
	v_readlane_b32 s53, v255, 5
	s_mov_b32 s54, s0
	s_barrier
	v_readlane_b32 s1, v255, 2
	s_branch .LBB0_1329
